# plus MLA max-tree/rsum-tree (reassociated f32 row sum), weight-conversion row prefetch, residual-epilogue h prefetch
# speedup vs baseline: 1.0622x; 1.0227x over previous
.LBB0_130:
	s_or_b64 exec, exec, s[12:13]
	v_lshrrev_b32_e32 v3, 2, v9
	v_and_b32_e32 v4, 48, v3
	s_waitcnt lgkmcnt(0)
	s_cmp_lg_u64 s[4:5], 0
	s_mul_i32 s17, s54, 0x12b0000
	s_cselect_b64 s[14:15], -1, 0
	v_ashrrev_i32_e32 v3, 31, v2
	s_add_u32 s6, s6, s17
	s_mul_hi_i32 s17, s54, 0x12b0000
	v_lshl_or_b32 v4, v1, 6, v4
	v_lshlrev_b32_e32 v5, 10, v10
	s_addc_u32 s7, s7, s17
	v_sub_u32_e32 v4, v4, v5
	v_lshlrev_b64 v[2:3], 2, v[2:3]
	s_movk_i32 s17, 0x4ac0
	v_mad_i64_i32 v[2:3], s[18:19], v4, s17, v[2:3]
	v_lshl_add_u64 v[2:3], s[6:7], 0, v[2:3]
	v_readlane_b32 s6, v254, 1
	v_readlane_b32 s7, v254, 2
	s_add_u32 s4, s4, s6
	v_ashrrev_i32_e32 v5, 31, v4
	s_addc_u32 s5, s5, s7
	v_bfe_u32 v7, v9, 6, 2
	v_lshl_add_u64 v[4:5], v[4:5], 2, s[4:5]
	v_mul_u32_u24_e32 v7, 0x1040, v7
	v_lshlrev_b32_e32 v6, 2, v6
	s_mov_b64 s[12:13], 0
	v_lshl_add_u64 v[4:5], v[4:5], 0, 8
	v_add3_u32 v11, v7, v6, v225
	s_and_saveexec_b64 s[98:99], s[10:11]
	v_add_co_u32_e32 v242, vcc, 0x12b4ac0, v2
	s_nop 1
	v_addc_co_u32_e32 v243, vcc, 0, v3, vcc
	global_load_dword v241, v[242:243], off
	v_add_co_u32_e32 v244, vcc, 0x12b9580, v2
	s_nop 1
	v_addc_co_u32_e32 v245, vcc, 0, v3, vcc
	global_load_dword v241, v[244:245], off
	v_add_co_u32_e32 v242, vcc, 0x12be040, v2
	s_nop 1
	v_addc_co_u32_e32 v243, vcc, 0, v3, vcc
	global_load_dword v241, v[242:243], off
	v_add_co_u32_e32 v244, vcc, 0x12c2b00, v2
	s_nop 1
	v_addc_co_u32_e32 v245, vcc, 0, v3, vcc
	global_load_dword v241, v[244:245], off
	v_add_co_u32_e32 v242, vcc, 0x12c75c0, v2
	s_nop 1
	v_addc_co_u32_e32 v243, vcc, 0, v3, vcc
	global_load_dword v241, v[242:243], off
	v_add_co_u32_e32 v244, vcc, 0x12cc080, v2
	s_nop 1
	v_addc_co_u32_e32 v245, vcc, 0, v3, vcc
	global_load_dword v241, v[244:245], off
	v_add_co_u32_e32 v242, vcc, 0x12d0b40, v2
	s_nop 1
	v_addc_co_u32_e32 v243, vcc, 0, v3, vcc
	global_load_dword v241, v[242:243], off
	v_add_co_u32_e32 v244, vcc, 0x12d5600, v2
	s_nop 1
	v_addc_co_u32_e32 v245, vcc, 0, v3, vcc
	global_load_dword v241, v[244:245], off
	v_add_co_u32_e32 v242, vcc, 0x12da0c0, v2
	s_nop 1
	v_addc_co_u32_e32 v243, vcc, 0, v3, vcc
	global_load_dword v241, v[242:243], off
	v_add_co_u32_e32 v244, vcc, 0x12deb80, v2
	s_nop 1
	v_addc_co_u32_e32 v245, vcc, 0, v3, vcc
	global_load_dword v241, v[244:245], off
	v_add_co_u32_e32 v242, vcc, 0x12e3640, v2
	s_nop 1
	v_addc_co_u32_e32 v243, vcc, 0, v3, vcc
	global_load_dword v241, v[242:243], off
	v_add_co_u32_e32 v244, vcc, 0x12e8100, v2
	s_nop 1
	v_addc_co_u32_e32 v245, vcc, 0, v3, vcc
	global_load_dword v241, v[244:245], off
	v_add_co_u32_e32 v242, vcc, 0x12ecbc0, v2
	s_nop 1
	v_addc_co_u32_e32 v243, vcc, 0, v3, vcc
	global_load_dword v241, v[242:243], off
	v_add_co_u32_e32 v244, vcc, 0x12f1680, v2
	s_nop 1
	v_addc_co_u32_e32 v245, vcc, 0, v3, vcc
	global_load_dword v241, v[244:245], off
	v_add_co_u32_e32 v242, vcc, 0x12f6140, v2
	s_nop 1
	v_addc_co_u32_e32 v243, vcc, 0, v3, vcc
	global_load_dword v241, v[242:243], off
	s_mov_b64 exec, s[98:99]
	s_barrier
	s_branch .LBB0_132

.LBB0_180:
	s_and_b64 vcc, exec, s[0:1]
	s_cbranch_vccz .LBB0_226
	v_lshl_add_u32 v1, s16, 1, v224
	s_movk_i32 s0, 0x1ff
	v_cmp_lt_i32_e32 vcc, s0, v1
	s_and_saveexec_b64 s[0:1], vcc
	s_xor_b64 s[0:1], exec, s[0:1]
	v_add_u32_e32 v1, 0xfffffe00, v1
	s_andn2_saveexec_b64 s[2:3], s[0:1]
	s_cbranch_execz .LBB0_203
	v_ashrrev_i32_e32 v2, 31, v1
	s_load_dwordx2 s[0:1], s[82:83], 0x70
	s_load_dwordx2 s[4:5], s[82:83], 0xf8
	s_load_dwordx2 s[6:7], s[82:83], 0x48
	v_lshrrev_b32_e32 v2, 27, v2
	v_add_u32_e32 v2, v1, v2
	v_mov_b32_e32 v13, v210
	v_readlane_b32 s8, v255, 11
	v_and_b32_e32 v4, 0x3ffffe0, v2
	v_lshlrev_b32_e32 v2, 1, v2
	v_readlane_b32 s9, v255, 12
	s_waitcnt lgkmcnt(0)
	s_add_u32 s0, s0, s8
	v_bfi_b32 v6, 63, v13, v2
	s_addc_u32 s1, s1, s9
	v_sub_u32_e32 v4, v1, v4
	v_ashrrev_i32_e32 v7, 31, v6
	v_and_b32_e32 v3, 63, v13
	v_and_b32_e32 v12, 0xffffffc0, v2
	v_lshlrev_b32_e32 v2, 6, v4
	v_lshrrev_b32_e32 v4, 2, v13
	v_lshl_add_u64 v[6:7], v[6:7], 2, s[0:1]
	v_bfe_u32 v5, v13, 6, 2
	v_readlane_b32 s0, v255, 9
	v_and_or_b32 v4, v4, 48, v2
	v_mul_u32_u24_e32 v5, 0x1040, v5
	v_lshlrev_b32_e32 v3, 2, v3
	v_readlane_b32 s1, v255, 10
	s_add_u32 s0, s6, s0
	v_add3_u32 v3, v5, v3, v225
	s_addc_u32 s1, s7, s1
	v_ashrrev_i32_e32 v5, 31, v4
	v_lshl_add_u64 v[8:9], v[4:5], 2, s[0:1]
	v_lshl_add_u64 v[8:9], v[8:9], 0, 8
	s_mov_b32 s8, 0
	v_add_u32_e32 v248, 0x200, v4
	v_add_u32_e32 v250, 0xfffffc00, v4
	v_cmp_gt_u32_e32 vcc, 0x600, v4
	s_nop 1
	v_cndmask_b32_e32 v250, v4, v250, vcc
	v_cmp_gt_u32_e32 vcc, 0x400, v4
	s_nop 1
	v_cndmask_b32_e32 v250, v250, v248, vcc
	v_ashrrev_i32_e32 v251, 31, v250
	v_lshlrev_b64 v[250:251], 12, v[250:251]
	v_lshl_add_u64 v[250:251], v[6:7], 0, v[250:251]
	global_load_dword v241, v[250:251], off
	v_add_co_u32_e32 v242, vcc, 0x1000, v250
	s_nop 1
	v_addc_co_u32_e32 v243, vcc, 0, v251, vcc
	global_load_dword v241, v[242:243], off
	v_add_co_u32_e32 v244, vcc, 0x2000, v250
	s_nop 1
	v_addc_co_u32_e32 v245, vcc, 0, v251, vcc
	global_load_dword v241, v[244:245], off
	v_add_co_u32_e32 v242, vcc, 0x3000, v250
	s_nop 1
	v_addc_co_u32_e32 v243, vcc, 0, v251, vcc
	global_load_dword v241, v[242:243], off
	v_add_co_u32_e32 v244, vcc, 0x4000, v250
	s_nop 1
	v_addc_co_u32_e32 v245, vcc, 0, v251, vcc
	global_load_dword v241, v[244:245], off
	v_add_co_u32_e32 v242, vcc, 0x5000, v250
	s_nop 1
	v_addc_co_u32_e32 v243, vcc, 0, v251, vcc
	global_load_dword v241, v[242:243], off
	v_add_co_u32_e32 v244, vcc, 0x6000, v250
	s_nop 1
	v_addc_co_u32_e32 v245, vcc, 0, v251, vcc
	global_load_dword v241, v[244:245], off
	v_add_co_u32_e32 v242, vcc, 0x7000, v250
	s_nop 1
	v_addc_co_u32_e32 v243, vcc, 0, v251, vcc
	global_load_dword v241, v[242:243], off
	v_add_co_u32_e32 v244, vcc, 0x8000, v250
	s_nop 1
	v_addc_co_u32_e32 v245, vcc, 0, v251, vcc
	global_load_dword v241, v[244:245], off
	v_add_co_u32_e32 v242, vcc, 0x9000, v250
	s_nop 1
	v_addc_co_u32_e32 v243, vcc, 0, v251, vcc
	global_load_dword v241, v[242:243], off
	v_add_co_u32_e32 v244, vcc, 0xa000, v250
	s_nop 1
	v_addc_co_u32_e32 v245, vcc, 0, v251, vcc
	global_load_dword v241, v[244:245], off
	v_add_co_u32_e32 v242, vcc, 0xb000, v250
	s_nop 1
	v_addc_co_u32_e32 v243, vcc, 0, v251, vcc
	global_load_dword v241, v[242:243], off
	v_add_co_u32_e32 v244, vcc, 0xc000, v250
	s_nop 1
	v_addc_co_u32_e32 v245, vcc, 0, v251, vcc
	global_load_dword v241, v[244:245], off
	v_add_co_u32_e32 v242, vcc, 0xd000, v250
	s_nop 1
	v_addc_co_u32_e32 v243, vcc, 0, v251, vcc
	global_load_dword v241, v[242:243], off
	v_add_co_u32_e32 v244, vcc, 0xe000, v250
	s_nop 1
	v_addc_co_u32_e32 v245, vcc, 0, v251, vcc
	global_load_dword v241, v[244:245], off
	v_add_co_u32_e32 v242, vcc, 0xf000, v250
	s_nop 1
	v_addc_co_u32_e32 v243, vcc, 0, v251, vcc
	global_load_dword v241, v[242:243], off
	s_barrier
	s_branch .LBB0_186

.LBB0_208:
	s_load_dwordx2 s[8:9], s[82:83], 0x100
	s_load_dwordx2 s[4:5], s[82:83], 0x78
	s_load_dwordx4 s[12:15], s[82:83], 0x80
	v_ashrrev_i32_e32 v2, 31, v1
	v_mov_b32_e32 v9, v210
	v_lshrrev_b32_e32 v2, 28, v2
	v_add_u32_e32 v2, v1, v2
	v_and_b32_e32 v10, 63, v9
	v_ashrrev_i32_e32 v8, 4, v2
	s_waitcnt lgkmcnt(0)
	v_mov_b32_e32 v2, s15
	v_mov_b32_e32 v3, s13
	v_cmp_gt_u32_e32 vcc, 32, v10
	v_mov_b32_e32 v4, s12
	v_and_b32_e32 v6, 31, v9
	v_cndmask_b32_e32 v3, v2, v3, vcc
	v_mov_b32_e32 v2, s14
	v_cndmask_b32_e32 v2, v2, v4, vcc
	v_lshrrev_b32_e32 v4, 2, v9
	v_and_b32_e32 v4, 48, v4
	v_readlane_b32 s14, v253, 59
	v_lshl_or_b32 v6, v8, 5, v6
	v_readlane_b32 s15, v253, 60
	v_lshl_or_b32 v4, v1, 6, v4
	v_lshlrev_b32_e32 v5, 10, v8
	v_ashrrev_i32_e32 v7, 31, v6
	v_lshl_add_u64 v[2:3], v[2:3], 0, s[14:15]
	v_sub_u32_e32 v4, v4, v5
	v_lshlrev_b64 v[6:7], 2, v[6:7]
	s_movk_i32 s14, 0x2c00
	v_mad_i64_i32 v[6:7], s[14:15], v4, s14, v[6:7]
	s_cmp_lg_u64 s[4:5], 0
	v_readlane_b32 s14, v255, 9
	s_cselect_b64 s[12:13], -1, 0
	v_readlane_b32 s15, v255, 10
	s_add_u32 s4, s4, s14
	v_ashrrev_i32_e32 v5, 31, v4
	v_lshl_add_u64 v[2:3], v[2:3], 0, v[6:7]
	s_addc_u32 s5, s5, s15
	v_bfe_u32 v6, v9, 6, 2
	v_lshl_add_u64 v[4:5], v[4:5], 2, s[4:5]
	v_mul_u32_u24_e32 v6, 0x1040, v6
	v_lshlrev_b32_e32 v7, 2, v10
	s_mov_b64 s[10:11], 0
	v_lshl_add_u64 v[4:5], v[4:5], 0, 8
	v_add3_u32 v10, v6, v7, v225
	v_add_co_u32_e32 v242, vcc, 0x2c00, v2
	s_nop 1
	v_addc_co_u32_e32 v243, vcc, 0, v3, vcc
	global_load_dword v241, v[242:243], off
	v_add_co_u32_e32 v244, vcc, 0x5800, v2
	s_nop 1
	v_addc_co_u32_e32 v245, vcc, 0, v3, vcc
	global_load_dword v241, v[244:245], off
	v_add_co_u32_e32 v242, vcc, 0x8400, v2
	s_nop 1
	v_addc_co_u32_e32 v243, vcc, 0, v3, vcc
	global_load_dword v241, v[242:243], off
	v_add_co_u32_e32 v244, vcc, 0xb000, v2
	s_nop 1
	v_addc_co_u32_e32 v245, vcc, 0, v3, vcc
	global_load_dword v241, v[244:245], off
	v_add_co_u32_e32 v242, vcc, 0xdc00, v2
	s_nop 1
	v_addc_co_u32_e32 v243, vcc, 0, v3, vcc
	global_load_dword v241, v[242:243], off
	v_add_co_u32_e32 v244, vcc, 0x10800, v2
	s_nop 1
	v_addc_co_u32_e32 v245, vcc, 0, v3, vcc
	global_load_dword v241, v[244:245], off
	v_add_co_u32_e32 v242, vcc, 0x13400, v2
	s_nop 1
	v_addc_co_u32_e32 v243, vcc, 0, v3, vcc
	global_load_dword v241, v[242:243], off
	v_add_co_u32_e32 v244, vcc, 0x16000, v2
	s_nop 1
	v_addc_co_u32_e32 v245, vcc, 0, v3, vcc
	global_load_dword v241, v[244:245], off
	v_add_co_u32_e32 v242, vcc, 0x18c00, v2
	s_nop 1
	v_addc_co_u32_e32 v243, vcc, 0, v3, vcc
	global_load_dword v241, v[242:243], off
	v_add_co_u32_e32 v244, vcc, 0x1b800, v2
	s_nop 1
	v_addc_co_u32_e32 v245, vcc, 0, v3, vcc
	global_load_dword v241, v[244:245], off
	v_add_co_u32_e32 v242, vcc, 0x1e400, v2
	s_nop 1
	v_addc_co_u32_e32 v243, vcc, 0, v3, vcc
	global_load_dword v241, v[242:243], off
	v_add_co_u32_e32 v244, vcc, 0x21000, v2
	s_nop 1
	v_addc_co_u32_e32 v245, vcc, 0, v3, vcc
	global_load_dword v241, v[244:245], off
	v_add_co_u32_e32 v242, vcc, 0x23c00, v2
	s_nop 1
	v_addc_co_u32_e32 v243, vcc, 0, v3, vcc
	global_load_dword v241, v[242:243], off
	v_add_co_u32_e32 v244, vcc, 0x26800, v2
	s_nop 1
	v_addc_co_u32_e32 v245, vcc, 0, v3, vcc
	global_load_dword v241, v[244:245], off
	v_add_co_u32_e32 v242, vcc, 0x29400, v2
	s_nop 1
	v_addc_co_u32_e32 v243, vcc, 0, v3, vcc
	global_load_dword v241, v[242:243], off
	s_barrier
	s_branch .LBB0_210

.LBB0_219:
	s_movk_i32 s4, 0x2c0
	v_cmp_gt_i32_e32 vcc, s4, v1
	s_and_saveexec_b64 s[4:5], vcc
	s_cbranch_execz .LBB0_223
	s_load_dwordx2 s[6:7], s[82:83], 0x90
	v_readlane_b32 s8, v253, 59
	v_mov_b32_e32 v19, v210
	v_readlane_b32 s9, v253, 60
	s_waitcnt lgkmcnt(0)
	s_add_u32 s6, s6, s8
	s_mov_b32 s8, 0x2e8ba2e9
	v_mul_hi_i32 v2, v1, s8
	v_lshrrev_b32_e32 v4, 31, v2
	v_ashrrev_i32_e32 v2, 3, v2
	v_add_u32_e32 v2, v2, v4
	v_mul_lo_u32 v4, v2, 44
	v_sub_u32_e32 v1, v1, v4
	v_lshlrev_b32_e32 v21, 6, v2
	v_lshlrev_b32_e32 v2, 6, v1
	v_lshrrev_b32_e32 v1, 2, v19
	v_and_b32_e32 v3, 63, v19
	v_and_b32_e32 v8, 48, v1
	v_or_b32_e32 v4, v3, v21
	v_or_b32_e32 v10, v8, v2
	s_addc_u32 s7, s7, s9
	v_ashrrev_i32_e32 v5, 31, v4
	v_or_b32_e32 v12, 2, v10
	v_or_b32_e32 v14, 2, v8
	v_or_b32_e32 v16, 4, v10
	v_or_b32_e32 v18, 4, v8
	v_or_b32_e32 v20, 6, v10
	v_or_b32_e32 v22, 6, v8
	v_lshl_add_u64 v[4:5], v[4:5], 2, s[6:7]
	v_lshl_add_u32 v6, v3, 2, v225
	v_mov_b32_e32 v1, v8
	v_mov_b32_e32 v3, v10
	v_mov_b32_e32 v7, v12
	v_mov_b32_e32 v9, v14
	v_mov_b32_e32 v11, v16
	v_mov_b32_e32 v13, v18
	v_mov_b32_e32 v15, v20
	v_mov_b32_e32 v17, v22
	s_mov_b32 s6, 1
	s_mov_b32 s7, 0
	s_mov_b32 s8, 16
	s_movk_i32 s9, 0x104
	v_mov_b32_e32 v250, v10
	v_ashrrev_i32_e32 v251, 31, v10
	v_lshlrev_b64 v[250:251], 12, v[250:251]
	v_lshl_add_u64 v[250:251], v[4:5], 0, v[250:251]
	v_add_co_u32_e32 v242, vcc, 0x2000, v250
	s_nop 1
	v_addc_co_u32_e32 v243, vcc, 0, v251, vcc
	global_load_dword v241, v[242:243], off
	v_add_co_u32_e32 v244, vcc, 0x3000, v250
	s_nop 1
	v_addc_co_u32_e32 v245, vcc, 0, v251, vcc
	global_load_dword v241, v[244:245], off
	v_add_co_u32_e32 v242, vcc, 0x4000, v250
	s_nop 1
	v_addc_co_u32_e32 v243, vcc, 0, v251, vcc
	global_load_dword v241, v[242:243], off
	v_add_co_u32_e32 v244, vcc, 0x5000, v250
	s_nop 1
	v_addc_co_u32_e32 v245, vcc, 0, v251, vcc
	global_load_dword v241, v[244:245], off
	v_add_co_u32_e32 v242, vcc, 0x6000, v250
	s_nop 1
	v_addc_co_u32_e32 v243, vcc, 0, v251, vcc
	global_load_dword v241, v[242:243], off
	v_add_co_u32_e32 v244, vcc, 0x7000, v250
	s_nop 1
	v_addc_co_u32_e32 v245, vcc, 0, v251, vcc
	global_load_dword v241, v[244:245], off
	v_add_co_u32_e32 v242, vcc, 0x8000, v250
	s_nop 1
	v_addc_co_u32_e32 v243, vcc, 0, v251, vcc
	global_load_dword v241, v[242:243], off
	v_add_co_u32_e32 v244, vcc, 0x9000, v250
	s_nop 1
	v_addc_co_u32_e32 v245, vcc, 0, v251, vcc
	global_load_dword v241, v[244:245], off
	v_add_co_u32_e32 v242, vcc, 0xa000, v250
	s_nop 1
	v_addc_co_u32_e32 v243, vcc, 0, v251, vcc
	global_load_dword v241, v[242:243], off
	v_add_co_u32_e32 v244, vcc, 0xb000, v250
	s_nop 1
	v_addc_co_u32_e32 v245, vcc, 0, v251, vcc
	global_load_dword v241, v[244:245], off
	v_add_co_u32_e32 v242, vcc, 0xc000, v250
	s_nop 1
	v_addc_co_u32_e32 v243, vcc, 0, v251, vcc
	global_load_dword v241, v[242:243], off
	v_add_co_u32_e32 v244, vcc, 0xd000, v250
	s_nop 1
	v_addc_co_u32_e32 v245, vcc, 0, v251, vcc
	global_load_dword v241, v[244:245], off
	v_add_co_u32_e32 v242, vcc, 0xe000, v250
	s_nop 1
	v_addc_co_u32_e32 v243, vcc, 0, v251, vcc
	global_load_dword v241, v[242:243], off
	v_add_co_u32_e32 v244, vcc, 0xf000, v250
	s_nop 1
	v_addc_co_u32_e32 v245, vcc, 0, v251, vcc
	global_load_dword v241, v[244:245], off
	s_barrier

.LBB0_238:
	s_or_b64 exec, exec, s[50:51]
	v_add_f32_e32 v3, v3, v4
	v_add_f32_e32 v5, v5, v6
	v_add_f32_e32 v7, v7, v8
	v_add_f32_e32 v9, v9, v10
	v_add_f32_e32 v11, v11, v12
	v_add_f32_e32 v13, v13, v14
	v_add_f32_e32 v15, v15, v80
	v_add_f32_e32 v81, v81, v82
	v_add_f32_e32 v83, v83, v84
	v_add_f32_e32 v85, v85, v86
	v_add_f32_e32 v87, v87, v88
	v_add_f32_e32 v89, v89, v90
	v_add_f32_e32 v91, v91, v92
	v_add_f32_e32 v93, v93, v94
	v_add_f32_e32 v95, v95, v96
	v_add_f32_e32 v97, v97, v98
	v_add_f32_e32 v48, v48, v49
	v_add_f32_e32 v50, v50, v51
	v_add_f32_e32 v52, v52, v53
	v_add_f32_e32 v54, v54, v55
	v_add_f32_e32 v56, v56, v57
	v_add_f32_e32 v58, v58, v59
	v_add_f32_e32 v60, v60, v61
	v_add_f32_e32 v62, v62, v63
	v_add_f32_e32 v64, v64, v65
	v_add_f32_e32 v66, v66, v67
	v_add_f32_e32 v68, v68, v69
	v_add_f32_e32 v70, v70, v71
	v_add_f32_e32 v72, v72, v73
	v_add_f32_e32 v74, v74, v75
	v_add_f32_e32 v76, v76, v77
	v_add_f32_e32 v78, v78, v79
	v_add_f32_e32 v3, v3, v5
	v_add_f32_e32 v7, v7, v9
	v_add_f32_e32 v11, v11, v13
	v_add_f32_e32 v15, v15, v81
	v_add_f32_e32 v83, v83, v85
	v_add_f32_e32 v87, v87, v89
	v_add_f32_e32 v91, v91, v93
	v_add_f32_e32 v95, v95, v97
	v_add_f32_e32 v48, v48, v50
	v_add_f32_e32 v52, v52, v54
	v_add_f32_e32 v56, v56, v58
	v_add_f32_e32 v60, v60, v62
	v_add_f32_e32 v64, v64, v66
	v_add_f32_e32 v68, v68, v70
	v_add_f32_e32 v72, v72, v74
	v_add_f32_e32 v76, v76, v78
	v_add_f32_e32 v3, v3, v7
	v_add_f32_e32 v11, v11, v15
	v_add_f32_e32 v83, v83, v87
	v_add_f32_e32 v91, v91, v95
	v_add_f32_e32 v48, v48, v52
	v_add_f32_e32 v56, v56, v60
	v_add_f32_e32 v64, v64, v68
	v_add_f32_e32 v72, v72, v76
	v_add_f32_e32 v3, v3, v11
	v_add_f32_e32 v83, v83, v91
	v_add_f32_e32 v48, v48, v56
	v_add_f32_e32 v64, v64, v72
	v_add_f32_e32 v3, v3, v83
	v_add_f32_e32 v48, v48, v64
	v_add_f32_e32 v3, v3, v48
	v_fmac_f32_e32 v3, v232, v2
	v_mov_b32_e32 v238, v1
	v_mov_b32_e32 v232, v3

.LBB0_250:
	s_or_b64 exec, exec, s[70:71]
	s_nop 3
	v_max3_f32 v1, v48, v49, v50
	v_max3_f32 v2, v80, v81, v82
	v_max3_f32 v3, v96, v97, v98
	v_max3_f32 v4, v64, v65, v66
	v_max3_f32 v1, v1, v51, v52
	v_max3_f32 v2, v2, v83, v84
	v_max3_f32 v3, v3, v99, v100
	v_max3_f32 v4, v4, v67, v68
	v_max3_f32 v1, v1, v53, v54
	v_max3_f32 v2, v2, v85, v86
	v_max3_f32 v3, v3, v101, v102
	v_max3_f32 v4, v4, v69, v70
	v_max3_f32 v1, v1, v55, v56
	v_max3_f32 v2, v2, v87, v88
	v_max3_f32 v3, v3, v103, v104
	v_max3_f32 v4, v4, v71, v72
	v_max3_f32 v1, v1, v57, v58
	v_max3_f32 v2, v2, v89, v90
	v_max3_f32 v3, v3, v105, v106
	v_max3_f32 v4, v4, v73, v74
	v_max3_f32 v1, v1, v59, v60
	v_max3_f32 v2, v2, v91, v92
	v_max3_f32 v3, v3, v107, v108
	v_max3_f32 v4, v4, v75, v76
	v_max3_f32 v1, v1, v61, v62
	v_max3_f32 v2, v2, v93, v94
	v_max3_f32 v3, v3, v109, v110
	v_max3_f32 v4, v4, v77, v78
	v_max_f32_e32 v1, v1, v63
	v_max_f32_e32 v2, v2, v95
	v_max_f32_e32 v3, v3, v111
	v_max_f32_e32 v4, v4, v79
	v_max3_f32 v1, v1, v2, v3
	v_max_f32_e32 v1, v1, v4
	v_and_b32_e32 v3, 64, v211
	v_xor_b32_e32 v2, 32, v211
	v_add_u32_e32 v3, 64, v3
	v_cmp_lt_i32_e32 vcc, v2, v3
	s_nop 1
	v_cndmask_b32_e32 v2, v211, v2, vcc
	v_lshlrev_b32_e32 v2, 2, v2
	ds_bpermute_b32 v2, v2, v1
	s_waitcnt lgkmcnt(0)
	v_max3_f32 v1, v238, v1, v2
	v_sub_f32_e32 v2, v238, v1
	v_exp_f32_e32 v2, v2
	v_cmp_gt_f32_e32 vcc, v1, v238
	s_cbranch_vccz .LBB0_252
	v_pk_mul_f32 v[46:47], v[46:47], v[2:3] op_sel_hi:[1,0]
	v_pk_mul_f32 v[44:45], v[44:45], v[2:3] op_sel_hi:[1,0]
	v_pk_mul_f32 v[42:43], v[42:43], v[2:3] op_sel_hi:[1,0]
	v_pk_mul_f32 v[40:41], v[40:41], v[2:3] op_sel_hi:[1,0]
	v_pk_mul_f32 v[38:39], v[38:39], v[2:3] op_sel_hi:[1,0]
	v_pk_mul_f32 v[36:37], v[36:37], v[2:3] op_sel_hi:[1,0]
	v_pk_mul_f32 v[34:35], v[34:35], v[2:3] op_sel_hi:[1,0]
	v_pk_mul_f32 v[32:33], v[32:33], v[2:3] op_sel_hi:[1,0]
	v_pk_mul_f32 v[30:31], v[30:31], v[2:3] op_sel_hi:[1,0]
	v_pk_mul_f32 v[28:29], v[28:29], v[2:3] op_sel_hi:[1,0]
	v_pk_mul_f32 v[26:27], v[26:27], v[2:3] op_sel_hi:[1,0]
	v_pk_mul_f32 v[24:25], v[24:25], v[2:3] op_sel_hi:[1,0]
	v_pk_mul_f32 v[22:23], v[22:23], v[2:3] op_sel_hi:[1,0]
	v_pk_mul_f32 v[20:21], v[20:21], v[2:3] op_sel_hi:[1,0]
	v_pk_mul_f32 v[18:19], v[18:19], v[2:3] op_sel_hi:[1,0]
	v_pk_mul_f32 v[16:17], v[16:17], v[2:3] op_sel_hi:[1,0]

.LBB0_290:
	s_or_b64 exec, exec, s[64:65]
	s_nop 3
	v_max3_f32 v1, v48, v49, v50
	v_max3_f32 v2, v80, v81, v82
	v_max3_f32 v3, v96, v97, v98
	v_max3_f32 v4, v64, v65, v66
	v_max3_f32 v1, v1, v51, v52
	v_max3_f32 v2, v2, v83, v84
	v_max3_f32 v3, v3, v99, v100
	v_max3_f32 v4, v4, v67, v68
	v_max3_f32 v1, v1, v53, v54
	v_max3_f32 v2, v2, v85, v86
	v_max3_f32 v3, v3, v101, v102
	v_max3_f32 v4, v4, v69, v70
	v_max3_f32 v1, v1, v55, v56
	v_max3_f32 v2, v2, v87, v88
	v_max3_f32 v3, v3, v103, v104
	v_max3_f32 v4, v4, v71, v72
	v_max3_f32 v1, v1, v57, v58
	v_max3_f32 v2, v2, v89, v90
	v_max3_f32 v3, v3, v105, v106
	v_max3_f32 v4, v4, v73, v74
	v_max3_f32 v1, v1, v59, v60
	v_max3_f32 v2, v2, v91, v92
	v_max3_f32 v3, v3, v107, v108
	v_max3_f32 v4, v4, v75, v76
	v_max3_f32 v1, v1, v61, v62
	v_max3_f32 v2, v2, v93, v94
	v_max3_f32 v3, v3, v109, v110
	v_max3_f32 v4, v4, v77, v78
	v_max_f32_e32 v1, v1, v63
	v_max_f32_e32 v2, v2, v95
	v_max_f32_e32 v3, v3, v111
	v_max_f32_e32 v4, v4, v79
	v_max3_f32 v1, v1, v2, v3
	v_max_f32_e32 v1, v1, v4
	v_and_b32_e32 v3, 64, v211
	v_xor_b32_e32 v2, 32, v211
	v_add_u32_e32 v3, 64, v3
	v_cmp_lt_i32_e32 vcc, v2, v3
	s_nop 1
	v_cndmask_b32_e32 v2, v211, v2, vcc
	v_lshlrev_b32_e32 v2, 2, v2
	ds_bpermute_b32 v2, v2, v1
	s_waitcnt lgkmcnt(0)
	v_max3_f32 v1, v238, v1, v2
	v_sub_f32_e32 v2, v238, v1
	v_exp_f32_e32 v2, v2
	v_cmp_gt_f32_e32 vcc, v1, v238
	s_cbranch_vccz .LBB0_292
	v_pk_mul_f32 v[46:47], v[46:47], v[2:3] op_sel_hi:[1,0]
	v_pk_mul_f32 v[44:45], v[44:45], v[2:3] op_sel_hi:[1,0]
	v_pk_mul_f32 v[42:43], v[42:43], v[2:3] op_sel_hi:[1,0]
	v_pk_mul_f32 v[40:41], v[40:41], v[2:3] op_sel_hi:[1,0]
	v_pk_mul_f32 v[38:39], v[38:39], v[2:3] op_sel_hi:[1,0]
	v_pk_mul_f32 v[36:37], v[36:37], v[2:3] op_sel_hi:[1,0]
	v_pk_mul_f32 v[34:35], v[34:35], v[2:3] op_sel_hi:[1,0]
	v_pk_mul_f32 v[32:33], v[32:33], v[2:3] op_sel_hi:[1,0]
	v_pk_mul_f32 v[30:31], v[30:31], v[2:3] op_sel_hi:[1,0]
	v_pk_mul_f32 v[28:29], v[28:29], v[2:3] op_sel_hi:[1,0]
	v_pk_mul_f32 v[26:27], v[26:27], v[2:3] op_sel_hi:[1,0]
	v_pk_mul_f32 v[24:25], v[24:25], v[2:3] op_sel_hi:[1,0]
	v_pk_mul_f32 v[22:23], v[22:23], v[2:3] op_sel_hi:[1,0]
	v_pk_mul_f32 v[20:21], v[20:21], v[2:3] op_sel_hi:[1,0]
	v_pk_mul_f32 v[18:19], v[18:19], v[2:3] op_sel_hi:[1,0]
	v_pk_mul_f32 v[16:17], v[16:17], v[2:3] op_sel_hi:[1,0]

.LBB0_471:
	v_mov_b32_e32 v134, v210
	s_waitcnt vmcnt(0)
	s_barrier
	s_movk_i32 s0, 0x210
	v_and_b32_e32 v136, 15, v134
	v_lshrrev_b32_e32 v135, 2, v134
	v_lshlrev_b32_e32 v134, 1, v134
	v_and_b32_e32 v135, 0xfffffcc, v135
	v_and_b32_e32 v134, 0x180, v134
	v_mad_u64_u32 v[134:135], s[0:1], v135, s0, v[134:135]
	v_lshl_or_b32 v134, v136, 2, v134
	ds_write2_b32 v134, v118, v126 offset1:16
	ds_write2_b32 v134, v119, v127 offset0:132 offset1:148
	v_add_u32_e32 v118, 0x400, v134
	ds_write2_b32 v118, v120, v128 offset0:8 offset1:24
	ds_write2_b32 v118, v121, v129 offset0:140 offset1:156
	v_add_u32_e32 v118, 0x2000, v134
	ds_write2_b32 v118, v110, v122 offset0:64 offset1:80
	ds_write2_b32 v118, v111, v123 offset0:196 offset1:212
	v_add_u32_e32 v110, 0x2400, v134
	ds_write2_b32 v110, v112, v124 offset0:72 offset1:88
	ds_write2_b32 v110, v113, v125 offset0:204 offset1:220
	v_add_u32_e32 v110, 0x4000, v134
	ds_write2_b32 v110, v102, v106 offset0:128 offset1:144
	v_add_u32_e32 v102, 0x4400, v134
	ds_write2_b32 v102, v103, v107 offset0:4 offset1:20
	ds_write2_b32 v102, v104, v108 offset0:136 offset1:152
	v_add_u32_e32 v102, 0x4800, v134
	ds_write2_b32 v102, v105, v109 offset0:12 offset1:28
	v_add_u32_e32 v102, 0x6000, v134
	ds_write2_b32 v102, v90, v98 offset0:192 offset1:208
	v_add_u32_e32 v90, 0x6400, v134
	ds_write2_b32 v90, v91, v99 offset0:68 offset1:84
	ds_write2_b32 v90, v92, v100 offset0:200 offset1:216
	v_add_u32_e32 v90, 0x6800, v134
	ds_write2_b32 v90, v93, v101 offset0:76 offset1:92
	v_add_u32_e32 v90, 0x12400, v134
	ds_write_b32 v90, v114
	v_add_u32_e32 v90, 0x12610, v134
	ds_write_b32 v90, v115
	v_add_u32_e32 v90, 0x12820, v134
	ds_write_b32 v90, v116
	v_add_u32_e32 v90, 0x12a30, v134
	ds_write_b32 v90, v117
	v_add_u32_e32 v90, 0x12440, v134
	ds_write_b32 v90, v94
	v_add_u32_e32 v90, 0x12650, v134
	ds_write_b32 v90, v95
	v_add_u32_e32 v90, 0x12860, v134
	ds_write_b32 v90, v96
	v_add_u32_e32 v90, 0x12a70, v134
	ds_write_b32 v90, v97
	v_add_u32_e32 v90, 0x14500, v134
	ds_write_b32 v90, v86
	v_add_u32_e32 v86, 0x14710, v134
	ds_write_b32 v86, v87
	v_add_u32_e32 v86, 0x14920, v134
	ds_write_b32 v86, v88
	v_add_u32_e32 v86, 0x14b30, v134
	ds_write_b32 v86, v89
	v_add_u32_e32 v86, 0x14540, v134
	ds_write_b32 v86, v82
	v_add_u32_e32 v82, 0x14750, v134
	ds_write_b32 v82, v83
	v_add_u32_e32 v82, 0x14960, v134
	ds_write_b32 v82, v84
	v_add_u32_e32 v82, 0x14b70, v134
	ds_write_b32 v82, v85
	v_add_u32_e32 v82, 0x16600, v134
	ds_write_b32 v82, v78
	v_add_u32_e32 v78, 0x16810, v134
	ds_write_b32 v78, v79
	v_add_u32_e32 v78, 0x16a20, v134
	ds_write_b32 v78, v80
	v_add_u32_e32 v78, 0x16c30, v134
	ds_write_b32 v78, v81
	v_add_u32_e32 v78, 0x16640, v134
	ds_write_b32 v78, v74
	v_add_u32_e32 v74, 0x16850, v134
	ds_write_b32 v74, v75
	v_add_u32_e32 v74, 0x16a60, v134
	ds_write_b32 v74, v76
	v_add_u32_e32 v74, 0x16c70, v134
	ds_write_b32 v74, v77
	v_add_u32_e32 v74, 0x18700, v134
	ds_write_b32 v74, v70
	v_add_u32_e32 v70, 0x18910, v134
	ds_write_b32 v70, v71
	v_add_u32_e32 v70, 0x18b20, v134
	ds_write_b32 v70, v72
	v_add_u32_e32 v70, 0x18d30, v134
	ds_write_b32 v70, v73
	v_add_u32_e32 v70, 0x18740, v134
	s_mul_hi_i32 s0, s10, 0x7e07e07f
	v_and_b32_e32 v76, 64, v211
	ds_write_b32 v70, v66
	v_add_u32_e32 v66, 0x18950, v134
	s_lshr_b32 s1, s0, 31
	s_ashr_i32 s0, s0, 12
	v_xor_b32_e32 v75, 1, v211
	v_add_u32_e32 v79, 64, v76
	ds_write_b32 v66, v67
	v_add_u32_e32 v66, 0x18b60, v134
	s_add_i32 s0, s0, s1
	v_cmp_lt_i32_e32 vcc, v75, v79
	ds_write_b32 v66, v68
	v_add_u32_e32 v66, 0x18d70, v134
	v_mov_b32_e32 v74, v210
	s_mulk_i32 s0, 0x2080
	v_cndmask_b32_e32 v75, v211, v75, vcc
	ds_write_b32 v66, v69
	s_waitcnt lgkmcnt(0)
	s_barrier
	s_sub_i32 s2, s10, s0
	s_load_dwordx2 s[0:1], s[82:83], 0xa8
	v_lshlrev_b32_e32 v76, 2, v75
	v_xor_b32_e32 v75, 2, v211
	v_ashrrev_i32_e32 v1, 8, v1
	v_cmp_lt_i32_e32 vcc, v75, v79
	v_lshl_add_u32 v130, s11, 1, v1
	v_lshlrev_b32_e32 v132, 7, v130
	v_cndmask_b32_e32 v75, v211, v75, vcc
	v_lshlrev_b32_e32 v77, 2, v75
	v_xor_b32_e32 v75, 4, v211
	v_ashrrev_i32_e32 v133, 31, v132
	v_lshlrev_b32_e32 v66, 3, v74
	v_cmp_lt_i32_e32 vcc, v75, v79
	v_and_b32_e32 v72, 0x78, v66
	s_waitcnt lgkmcnt(0)
	v_lshl_add_u64 v[66:67], v[132:133], 2, s[0:1]
	s_load_dwordx2 s[0:1], s[82:83], 0x130
	v_cndmask_b32_e32 v75, v211, v75, vcc
	v_lshlrev_b32_e32 v78, 2, v75
	v_xor_b32_e32 v75, 8, v211
	v_cmp_lt_i32_e32 vcc, v75, v79
	v_lshlrev_b32_e32 v196, 2, v72
	v_bfe_u32 v80, v74, 4, 4
	v_cndmask_b32_e32 v75, v211, v75, vcc
	v_lshlrev_b32_e32 v79, 2, v75
	v_and_b32_e32 v75, 15, v74
	v_mul_i32_i24_e32 v1, 0x12400, v1
	v_lshl_add_u64 v[70:71], v[66:67], 0, v[196:197]
	s_waitcnt lgkmcnt(0)
	v_lshl_add_u64 v[68:69], v[132:133], 1, s[0:1]
	v_lshlrev_b32_e32 v196, 1, v72
	v_cmp_eq_u32_e32 vcc, 0, v75
	v_mul_u32_u24_e32 v74, 0x210, v80
	v_lshlrev_b32_e32 v75, 5, v75
	v_ashrrev_i32_e32 v131, 31, v130
	v_lshl_add_u64 v[72:73], v[68:69], 0, v[196:197]
	s_mov_b32 s3, 0
	v_add3_u32 v81, v1, v74, v75
	v_add_u32_e32 v82, s10, v80
	v_ashrrev_i32_e32 v83, 31, v82
	v_lshlrev_b64 v[82:83], 12, v[82:83]
	v_lshl_add_u64 v[82:83], v[70:71], 0, v[82:83]
	s_mov_b64 s[98:99], 0x10000
	v_lshl_add_u64 v[84:85], v[82:83], 0, s[98:99]
	global_load_dword v86, v[84:85], off
	s_mov_b64 s[98:99], 0x20000
	v_lshl_add_u64 v[84:85], v[82:83], 0, s[98:99]
	global_load_dword v86, v[84:85], off
	s_mov_b64 s[98:99], 0x30000
	v_lshl_add_u64 v[84:85], v[82:83], 0, s[98:99]
	global_load_dword v86, v[84:85], off
	s_mov_b64 s[98:99], 0x40000
	v_lshl_add_u64 v[84:85], v[82:83], 0, s[98:99]
	global_load_dword v86, v[84:85], off
	s_mov_b64 s[98:99], 0x50000
	v_lshl_add_u64 v[84:85], v[82:83], 0, s[98:99]
	global_load_dword v86, v[84:85], off
	s_mov_b64 s[98:99], 0x60000
	v_lshl_add_u64 v[84:85], v[82:83], 0, s[98:99]
	global_load_dword v86, v[84:85], off
	s_mov_b64 s[98:99], 0x70000
	v_lshl_add_u64 v[84:85], v[82:83], 0, s[98:99]
	global_load_dword v86, v[84:85], off
	s_branch .LBB0_473

.LBB0_475:
	v_mov_b32_e32 v70, v210
	s_waitcnt lgkmcnt(0)
	s_barrier
	s_movk_i32 s0, 0x210
	v_and_b32_e32 v72, 15, v70
	v_lshrrev_b32_e32 v71, 2, v70
	v_lshlrev_b32_e32 v70, 1, v70
	v_and_b32_e32 v71, 0xfffffcc, v71
	v_and_b32_e32 v70, 0x180, v70
	v_mad_u64_u32 v[70:71], s[0:1], v71, s0, v[70:71]
	v_lshl_or_b32 v70, v72, 2, v70
	ds_write2_b32 v70, v54, v62 offset1:16
	ds_write2_b32 v70, v55, v63 offset0:132 offset1:148
	v_add_u32_e32 v54, 0x400, v70
	ds_write2_b32 v54, v56, v64 offset0:8 offset1:24
	ds_write2_b32 v54, v57, v65 offset0:140 offset1:156
	v_add_u32_e32 v54, 0x2000, v70
	ds_write2_b32 v54, v50, v58 offset0:64 offset1:80
	ds_write2_b32 v54, v51, v59 offset0:196 offset1:212
	v_add_u32_e32 v50, 0x2400, v70
	ds_write2_b32 v50, v52, v60 offset0:72 offset1:88
	ds_write2_b32 v50, v53, v61 offset0:204 offset1:220
	v_add_u32_e32 v50, 0x4000, v70
	ds_write2_b32 v50, v42, v46 offset0:128 offset1:144
	v_add_u32_e32 v42, 0x4400, v70
	ds_write2_b32 v42, v43, v47 offset0:4 offset1:20
	ds_write2_b32 v42, v44, v48 offset0:136 offset1:152
	v_add_u32_e32 v42, 0x4800, v70
	ds_write2_b32 v42, v45, v49 offset0:12 offset1:28
	v_add_u32_e32 v42, 0x6000, v70
	ds_write2_b32 v42, v34, v38 offset0:192 offset1:208
	v_add_u32_e32 v34, 0x6400, v70
	ds_write2_b32 v34, v35, v39 offset0:68 offset1:84
	ds_write2_b32 v34, v36, v40 offset0:200 offset1:216
	v_add_u32_e32 v34, 0x6800, v70
	ds_write2_b32 v34, v37, v41 offset0:76 offset1:92
	v_add_u32_e32 v34, 0x12400, v70
	ds_write_b32 v34, v30
	v_add_u32_e32 v30, 0x12610, v70
	ds_write_b32 v30, v31
	v_add_u32_e32 v30, 0x12820, v70
	ds_write_b32 v30, v32
	v_add_u32_e32 v30, 0x12a30, v70
	ds_write_b32 v30, v33
	v_add_u32_e32 v30, 0x12440, v70
	ds_write_b32 v30, v26
	v_add_u32_e32 v26, 0x12650, v70
	ds_write_b32 v26, v27
	v_add_u32_e32 v26, 0x12860, v70
	ds_write_b32 v26, v28
	v_add_u32_e32 v26, 0x12a70, v70
	ds_write_b32 v26, v29
	v_add_u32_e32 v26, 0x14500, v70
	ds_write_b32 v26, v22
	v_add_u32_e32 v22, 0x14710, v70
	ds_write_b32 v22, v23
	v_add_u32_e32 v22, 0x14920, v70
	ds_write_b32 v22, v24
	v_add_u32_e32 v22, 0x14b30, v70
	ds_write_b32 v22, v25
	v_add_u32_e32 v22, 0x14540, v70
	ds_write_b32 v22, v18
	v_add_u32_e32 v18, 0x14750, v70
	ds_write_b32 v18, v19
	v_add_u32_e32 v18, 0x14960, v70
	ds_write_b32 v18, v20
	v_add_u32_e32 v18, 0x14b70, v70
	ds_write_b32 v18, v21
	v_add_u32_e32 v18, 0x16600, v70
	ds_write_b32 v18, v14
	v_add_u32_e32 v14, 0x16810, v70
	ds_write_b32 v14, v15
	v_add_u32_e32 v14, 0x16a20, v70
	ds_write_b32 v14, v16
	v_add_u32_e32 v14, 0x16c30, v70
	ds_write_b32 v14, v17
	v_add_u32_e32 v14, 0x16640, v70
	ds_write_b32 v14, v10
	v_add_u32_e32 v10, 0x16850, v70
	ds_write_b32 v10, v11
	v_add_u32_e32 v10, 0x16a60, v70
	ds_write_b32 v10, v12
	v_add_u32_e32 v10, 0x16c70, v70
	ds_write_b32 v10, v13
	v_add_u32_e32 v10, 0x18700, v70
	ds_write_b32 v10, v6
	v_add_u32_e32 v6, 0x18910, v70
	ds_write_b32 v6, v7
	v_add_u32_e32 v6, 0x18b20, v70
	ds_write_b32 v6, v8
	v_add_u32_e32 v6, 0x18d30, v70
	ds_write_b32 v6, v9
	v_add_u32_e32 v6, 0x18740, v70
	ds_write_b32 v6, v2
	v_add_u32_e32 v2, 0x18950, v70
	ds_write_b32 v2, v3
	v_add_u32_e32 v2, 0x18b60, v70
	ds_write_b32 v2, v4
	v_add_u32_e32 v2, 0x18d70, v70
	v_mov_b32_e32 v6, v210
	s_bitset1_b32 s10, 7
	ds_write_b32 v2, v5
	s_waitcnt lgkmcnt(0)
	s_barrier
	s_mul_hi_i32 s0, s10, 0x7e07e07f
	v_lshlrev_b32_e32 v2, 3, v6
	s_lshr_b32 s1, s0, 31
	s_ashr_i32 s0, s0, 12
	v_and_b32_e32 v4, 0x78, v2
	s_add_i32 s0, s0, s1
	v_lshlrev_b32_e32 v196, 2, v4
	v_and_b32_e32 v7, 15, v6
	v_bfe_u32 v8, v6, 4, 4
	s_mulk_i32 s0, 0x2080
	v_lshl_add_u64 v[2:3], v[66:67], 0, v[196:197]
	v_lshlrev_b32_e32 v196, 1, v4
	v_cmp_eq_u32_e32 vcc, 0, v7
	v_mul_u32_u24_e32 v6, 0x210, v8
	v_lshlrev_b32_e32 v7, 5, v7
	s_sub_i32 s2, s10, s0
	v_lshl_add_u64 v[4:5], v[68:69], 0, v[196:197]
	s_mov_b32 s3, 0
	v_add3_u32 v1, v1, v6, v7
	v_add_u32_e32 v10, s10, v8
	v_ashrrev_i32_e32 v11, 31, v10
	v_lshlrev_b64 v[10:11], 12, v[10:11]
	v_lshl_add_u64 v[10:11], v[2:3], 0, v[10:11]
	s_mov_b64 s[98:99], 0x10000
	v_lshl_add_u64 v[12:13], v[10:11], 0, s[98:99]
	global_load_dword v14, v[12:13], off
	s_mov_b64 s[98:99], 0x20000
	v_lshl_add_u64 v[12:13], v[10:11], 0, s[98:99]
	global_load_dword v14, v[12:13], off
	s_mov_b64 s[98:99], 0x30000
	v_lshl_add_u64 v[12:13], v[10:11], 0, s[98:99]
	global_load_dword v14, v[12:13], off
	s_mov_b64 s[98:99], 0x40000
	v_lshl_add_u64 v[12:13], v[10:11], 0, s[98:99]
	global_load_dword v14, v[12:13], off
	s_mov_b64 s[98:99], 0x50000
	v_lshl_add_u64 v[12:13], v[10:11], 0, s[98:99]
	global_load_dword v14, v[12:13], off
	s_mov_b64 s[98:99], 0x60000
	v_lshl_add_u64 v[12:13], v[10:11], 0, s[98:99]
	global_load_dword v14, v[12:13], off
	s_mov_b64 s[98:99], 0x70000
	v_lshl_add_u64 v[12:13], v[10:11], 0, s[98:99]
	global_load_dword v14, v[12:13], off
	s_branch .LBB0_477

.LBB0_489:
	v_ashrrev_i32_e32 v1, 8, v1
	v_lshl_add_u32 v130, s12, 1, v1
	v_mul_i32_i24_e32 v134, 0x12400, v1
	v_mov_b32_e32 v1, v210
	s_waitcnt vmcnt(0)
	s_barrier
	s_movk_i32 s0, 0x210
	v_and_b32_e32 v135, 15, v1
	v_lshrrev_b32_e32 v136, 2, v1
	v_lshlrev_b32_e32 v1, 1, v1
	v_and_b32_e32 v137, 0xfffffcc, v136
	v_and_b32_e32 v136, 0x180, v1
	v_mad_u64_u32 v[136:137], s[0:1], v137, s0, v[136:137]
	v_lshl_or_b32 v1, v135, 2, v136
	ds_write2_b32 v1, v118, v126 offset1:16
	ds_write2_b32 v1, v119, v127 offset0:132 offset1:148
	v_add_u32_e32 v118, 0x400, v1
	ds_write2_b32 v118, v120, v128 offset0:8 offset1:24
	ds_write2_b32 v118, v121, v129 offset0:140 offset1:156
	v_add_u32_e32 v118, 0x2000, v1
	ds_write2_b32 v118, v110, v122 offset0:64 offset1:80
	ds_write2_b32 v118, v111, v123 offset0:196 offset1:212
	v_add_u32_e32 v110, 0x2400, v1
	ds_write2_b32 v110, v112, v124 offset0:72 offset1:88
	ds_write2_b32 v110, v113, v125 offset0:204 offset1:220
	v_add_u32_e32 v110, 0x4000, v1
	ds_write2_b32 v110, v102, v106 offset0:128 offset1:144
	v_add_u32_e32 v102, 0x4400, v1
	ds_write2_b32 v102, v103, v107 offset0:4 offset1:20
	ds_write2_b32 v102, v104, v108 offset0:136 offset1:152
	v_add_u32_e32 v102, 0x4800, v1
	ds_write2_b32 v102, v105, v109 offset0:12 offset1:28
	v_add_u32_e32 v102, 0x6000, v1
	ds_write2_b32 v102, v90, v98 offset0:192 offset1:208
	v_add_u32_e32 v90, 0x6400, v1
	ds_write2_b32 v90, v91, v99 offset0:68 offset1:84
	ds_write2_b32 v90, v92, v100 offset0:200 offset1:216
	v_add_u32_e32 v90, 0x6800, v1
	ds_write2_b32 v90, v93, v101 offset0:76 offset1:92
	v_add_u32_e32 v90, 0x12400, v1
	ds_write_b32 v90, v114
	v_add_u32_e32 v90, 0x12610, v1
	ds_write_b32 v90, v115
	v_add_u32_e32 v90, 0x12820, v1
	ds_write_b32 v90, v116
	v_add_u32_e32 v90, 0x12a30, v1
	ds_write_b32 v90, v117
	v_add_u32_e32 v90, 0x12440, v1
	ds_write_b32 v90, v94
	v_add_u32_e32 v90, 0x12650, v1
	ds_write_b32 v90, v95
	v_add_u32_e32 v90, 0x12860, v1
	ds_write_b32 v90, v96
	v_add_u32_e32 v90, 0x12a70, v1
	ds_write_b32 v90, v97
	v_add_u32_e32 v90, 0x14500, v1
	ds_write_b32 v90, v86
	v_add_u32_e32 v86, 0x14710, v1
	ds_write_b32 v86, v87
	v_add_u32_e32 v86, 0x14920, v1
	ds_write_b32 v86, v88
	v_add_u32_e32 v86, 0x14b30, v1
	ds_write_b32 v86, v89
	v_add_u32_e32 v86, 0x14540, v1
	ds_write_b32 v86, v82
	v_add_u32_e32 v82, 0x14750, v1
	ds_write_b32 v82, v83
	v_add_u32_e32 v82, 0x14960, v1
	ds_write_b32 v82, v84
	v_add_u32_e32 v82, 0x14b70, v1
	ds_write_b32 v82, v85
	v_add_u32_e32 v82, 0x16600, v1
	ds_write_b32 v82, v78
	v_add_u32_e32 v78, 0x16810, v1
	ds_write_b32 v78, v79
	v_add_u32_e32 v78, 0x16a20, v1
	ds_write_b32 v78, v80
	v_add_u32_e32 v78, 0x16c30, v1
	ds_write_b32 v78, v81
	v_add_u32_e32 v78, 0x16640, v1
	ds_write_b32 v78, v74
	v_add_u32_e32 v74, 0x16850, v1
	ds_write_b32 v74, v75
	v_add_u32_e32 v74, 0x16a60, v1
	ds_write_b32 v74, v76
	v_add_u32_e32 v74, 0x16c70, v1
	ds_write_b32 v74, v77
	v_add_u32_e32 v74, 0x18700, v1
	ds_write_b32 v74, v70
	v_add_u32_e32 v70, 0x18910, v1
	ds_write_b32 v70, v71
	v_add_u32_e32 v70, 0x18b20, v1
	ds_write_b32 v70, v72
	v_add_u32_e32 v70, 0x18d30, v1
	ds_write_b32 v70, v73
	v_add_u32_e32 v70, 0x18740, v1
	ds_write_b32 v70, v66
	v_add_u32_e32 v66, 0x18950, v1
	ds_write_b32 v66, v67
	v_add_u32_e32 v66, 0x18b60, v1
	v_add_u32_e32 v1, 0x18d70, v1
	v_and_b32_e32 v67, 64, v211
	ds_write_b32 v1, v69
	v_xor_b32_e32 v1, 1, v211
	v_add_u32_e32 v67, 64, v67
	ds_write_b32 v66, v68
	v_cmp_lt_i32_e32 vcc, v1, v67
	v_xor_b32_e32 v68, 2, v211
	v_mov_b32_e32 v66, v210
	v_cndmask_b32_e32 v1, v211, v1, vcc
	v_cmp_lt_i32_e32 vcc, v68, v67
	s_lshl_b32 s6, s11, 8
	s_waitcnt lgkmcnt(0)
	v_cndmask_b32_e32 v68, v211, v68, vcc
	v_lshlrev_b32_e32 v72, 2, v68
	v_xor_b32_e32 v68, 4, v211
	v_cmp_lt_i32_e32 vcc, v68, v67
	s_barrier
	s_nop 0
	v_cndmask_b32_e32 v68, v211, v68, vcc
	v_lshlrev_b32_e32 v73, 2, v68
	v_xor_b32_e32 v68, 8, v211
	v_bfe_u32 v75, v66, 4, 4
	v_cmp_lt_i32_e32 vcc, v68, v67
	v_and_b32_e32 v70, 15, v66
	v_or_b32_e32 v196, s6, v75
	s_load_dwordx2 s[2:3], s[82:83], 0xa8
	s_load_dwordx2 s[4:5], s[82:83], 0x130
	v_cndmask_b32_e32 v67, v211, v68, vcc
	v_lshlrev_b64 v[68:69], 11, v[196:197]
	v_mul_u32_u24_e32 v71, 0x210, v75
	v_lshlrev_b32_e32 v77, 5, v70
	v_lshlrev_b32_e32 v132, 7, v130
	v_cmp_eq_u32_e32 vcc, 0, v70
	v_lshl_or_b32 v68, v70, 4, v68
	v_add3_u32 v76, v134, v71, v77
	v_lshlrev_b64 v[70:71], 12, v[196:197]
	v_ashrrev_i32_e32 v133, 31, v132
	v_or_b32_e32 v70, v70, v77
	s_add_i32 s0, s6, 0xffffdf80
	v_lshl_add_u64 v[70:71], v[132:133], 2, v[70:71]
	v_ashrrev_i32_e32 v131, 31, v130
	s_cmpk_lt_u32 s10, 0x84
	v_lshlrev_b32_e32 v74, 2, v67
	v_lshlrev_b64 v[66:67], 5, v[196:197]
	v_lshl_add_u64 v[68:69], v[132:133], 1, v[68:69]
	s_waitcnt lgkmcnt(0)
	v_lshl_add_u64 v[70:71], s[2:3], 0, v[70:71]
	s_cselect_b32 s7, s6, s0
	s_mov_b32 s8, 0
	v_lshlrev_b32_e32 v1, 2, v1
	v_lshl_add_u64 v[66:67], v[130:131], 2, v[66:67]
	v_lshl_add_u64 v[68:69], s[4:5], 0, v[68:69]
	v_lshl_add_u64 v[70:71], v[70:71], 0, 16
	s_mov_b64 s[98:99], 0x10000
	v_lshl_add_u64 v[78:79], v[70:71], 0, s[98:99]
	global_load_dword v80, v[78:79], off
	s_mov_b64 s[98:99], 0x20000
	v_lshl_add_u64 v[78:79], v[70:71], 0, s[98:99]
	global_load_dword v80, v[78:79], off
	s_mov_b64 s[98:99], 0x30000
	v_lshl_add_u64 v[78:79], v[70:71], 0, s[98:99]
	global_load_dword v80, v[78:79], off
	s_mov_b64 s[98:99], 0x40000
	v_lshl_add_u64 v[78:79], v[70:71], 0, s[98:99]
	global_load_dword v80, v[78:79], off
	s_mov_b64 s[98:99], 0x50000
	v_lshl_add_u64 v[78:79], v[70:71], 0, s[98:99]
	global_load_dword v80, v[78:79], off
	s_mov_b64 s[98:99], 0x60000
	v_lshl_add_u64 v[78:79], v[70:71], 0, s[98:99]
	global_load_dword v80, v[78:79], off
	s_mov_b64 s[98:99], 0x70000
	v_lshl_add_u64 v[78:79], v[70:71], 0, s[98:99]
	global_load_dword v80, v[78:79], off
	s_branch .LBB0_491

.LBB0_493:
	v_mov_b32_e32 v70, v210
	s_waitcnt lgkmcnt(0)
	s_barrier
	s_movk_i32 s0, 0x210
	v_and_b32_e32 v75, 15, v70
	v_lshrrev_b32_e32 v71, 2, v70
	v_lshlrev_b32_e32 v70, 1, v70
	v_and_b32_e32 v71, 0xfffffcc, v71
	v_and_b32_e32 v70, 0x180, v70
	v_mad_u64_u32 v[70:71], s[0:1], v71, s0, v[70:71]
	v_lshl_or_b32 v70, v75, 2, v70
	ds_write2_b32 v70, v54, v62 offset1:16
	ds_write2_b32 v70, v55, v63 offset0:132 offset1:148
	v_add_u32_e32 v54, 0x400, v70
	ds_write2_b32 v54, v56, v64 offset0:8 offset1:24
	ds_write2_b32 v54, v57, v65 offset0:140 offset1:156
	v_add_u32_e32 v54, 0x2000, v70
	ds_write2_b32 v54, v50, v58 offset0:64 offset1:80
	ds_write2_b32 v54, v51, v59 offset0:196 offset1:212
	v_add_u32_e32 v50, 0x2400, v70
	ds_write2_b32 v50, v52, v60 offset0:72 offset1:88
	ds_write2_b32 v50, v53, v61 offset0:204 offset1:220
	v_add_u32_e32 v50, 0x4000, v70
	ds_write2_b32 v50, v42, v46 offset0:128 offset1:144
	v_add_u32_e32 v42, 0x4400, v70
	ds_write2_b32 v42, v43, v47 offset0:4 offset1:20
	ds_write2_b32 v42, v44, v48 offset0:136 offset1:152
	v_add_u32_e32 v42, 0x4800, v70
	ds_write2_b32 v42, v45, v49 offset0:12 offset1:28
	v_add_u32_e32 v42, 0x6000, v70
	ds_write2_b32 v42, v34, v38 offset0:192 offset1:208
	v_add_u32_e32 v34, 0x6400, v70
	ds_write2_b32 v34, v35, v39 offset0:68 offset1:84
	ds_write2_b32 v34, v36, v40 offset0:200 offset1:216
	v_add_u32_e32 v34, 0x6800, v70
	ds_write2_b32 v34, v37, v41 offset0:76 offset1:92
	v_add_u32_e32 v34, 0x12400, v70
	ds_write_b32 v34, v30
	v_add_u32_e32 v30, 0x12610, v70
	ds_write_b32 v30, v31
	v_add_u32_e32 v30, 0x12820, v70
	ds_write_b32 v30, v32
	v_add_u32_e32 v30, 0x12a30, v70
	ds_write_b32 v30, v33
	v_add_u32_e32 v30, 0x12440, v70
	ds_write_b32 v30, v26
	v_add_u32_e32 v26, 0x12650, v70
	ds_write_b32 v26, v27
	v_add_u32_e32 v26, 0x12860, v70
	ds_write_b32 v26, v28
	v_add_u32_e32 v26, 0x12a70, v70
	ds_write_b32 v26, v29
	v_add_u32_e32 v26, 0x14500, v70
	ds_write_b32 v26, v22
	v_add_u32_e32 v22, 0x14710, v70
	ds_write_b32 v22, v23
	v_add_u32_e32 v22, 0x14920, v70
	ds_write_b32 v22, v24
	v_add_u32_e32 v22, 0x14b30, v70
	ds_write_b32 v22, v25
	v_add_u32_e32 v22, 0x14540, v70
	ds_write_b32 v22, v18
	v_add_u32_e32 v18, 0x14750, v70
	ds_write_b32 v18, v19
	v_add_u32_e32 v18, 0x14960, v70
	ds_write_b32 v18, v20
	v_add_u32_e32 v18, 0x14b70, v70
	ds_write_b32 v18, v21
	v_add_u32_e32 v18, 0x16600, v70
	ds_write_b32 v18, v14
	v_add_u32_e32 v14, 0x16810, v70
	ds_write_b32 v14, v15
	v_add_u32_e32 v14, 0x16a20, v70
	ds_write_b32 v14, v16
	v_add_u32_e32 v14, 0x16c30, v70
	ds_write_b32 v14, v17
	v_add_u32_e32 v14, 0x16640, v70
	ds_write_b32 v14, v10
	v_add_u32_e32 v10, 0x16850, v70
	ds_write_b32 v10, v11
	v_add_u32_e32 v10, 0x16a60, v70
	ds_write_b32 v10, v12
	v_add_u32_e32 v10, 0x16c70, v70
	ds_write_b32 v10, v13
	v_add_u32_e32 v10, 0x18700, v70
	ds_write_b32 v10, v6
	v_add_u32_e32 v6, 0x18910, v70
	ds_write_b32 v6, v7
	v_add_u32_e32 v6, 0x18b20, v70
	ds_write_b32 v6, v8
	v_add_u32_e32 v6, 0x18d30, v70
	ds_write_b32 v6, v9
	v_add_u32_e32 v6, 0x18740, v70
	ds_write_b32 v6, v2
	v_add_u32_e32 v2, 0x18950, v70
	ds_write_b32 v2, v3
	v_add_u32_e32 v2, 0x18b60, v70
	ds_write_b32 v2, v4
	v_add_u32_e32 v2, 0x18d70, v70
	v_mov_b32_e32 v6, v210
	ds_write_b32 v2, v5
	s_waitcnt lgkmcnt(0)
	s_barrier
	s_bitset1_b32 s6, 7
	v_lshlrev_b32_e32 v2, 3, v6
	s_mul_hi_u32 s0, s6, 0xfc0fc0fd
	v_and_b32_e32 v4, 0x78, v2
	v_lshl_add_u64 v[66:67], v[132:133], 2, s[2:3]
	s_lshr_b32 s0, s0, 13
	v_lshlrev_b32_e32 v196, 2, v4
	v_and_b32_e32 v7, 15, v6
	v_bfe_u32 v6, v6, 4, 4
	v_lshl_add_u64 v[68:69], v[132:133], 1, s[4:5]
	s_mulk_i32 s0, 0x2080
	v_lshl_add_u64 v[2:3], v[66:67], 0, v[196:197]
	v_lshlrev_b32_e32 v196, 1, v4
	v_cmp_eq_u32_e32 vcc, 0, v7
	v_mul_u32_u24_e32 v8, 0x210, v6
	v_lshlrev_b32_e32 v7, 5, v7
	s_sub_i32 s2, s6, s0
	v_lshl_add_u64 v[4:5], v[68:69], 0, v[196:197]
	s_mov_b32 s3, 0
	v_add3_u32 v7, v134, v8, v7
	v_add_u32_e32 v8, s6, v6
	v_mov_b32_e32 v9, 0
	v_lshlrev_b64 v[8:9], 12, v[8:9]
	v_lshl_add_u64 v[8:9], v[2:3], 0, v[8:9]
	s_mov_b64 s[98:99], 0x10000
	v_lshl_add_u64 v[10:11], v[8:9], 0, s[98:99]
	global_load_dword v12, v[10:11], off
	s_mov_b64 s[98:99], 0x20000
	v_lshl_add_u64 v[10:11], v[8:9], 0, s[98:99]
	global_load_dword v12, v[10:11], off
	s_mov_b64 s[98:99], 0x30000
	v_lshl_add_u64 v[10:11], v[8:9], 0, s[98:99]
	global_load_dword v12, v[10:11], off
	s_mov_b64 s[98:99], 0x40000
	v_lshl_add_u64 v[10:11], v[8:9], 0, s[98:99]
	global_load_dword v12, v[10:11], off
	s_mov_b64 s[98:99], 0x50000
	v_lshl_add_u64 v[10:11], v[8:9], 0, s[98:99]
	global_load_dword v12, v[10:11], off
	s_mov_b64 s[98:99], 0x60000
	v_lshl_add_u64 v[10:11], v[8:9], 0, s[98:99]
	global_load_dword v12, v[10:11], off
	s_mov_b64 s[98:99], 0x70000
	v_lshl_add_u64 v[10:11], v[8:9], 0, s[98:99]
	global_load_dword v12, v[10:11], off
	s_branch .LBB0_495
